# gdn_out combine items: the eight carried-state (SN) tile loads issued together up front instead of one load-wait per tile
# baseline (speedup 1.0000x reference)
; DI unsigned pk2(float lo, float hi) { const hwf2_t v = {lo, hi}; const hwbf2_t b = __builtin_convertvector(v, hwbf2_t); return __builtin_bit_cast(unsigned, b); }
; DI float lo16(unsigned w) { return __uint_as_float(w << 16); }
; DI float hi16(unsigned w) { return __uint_as_float(w & 0xffff0000u); }
; DI void lds_barrier() { asm volatile("s_waitcnt lgkmcnt(0)" ::: "memory"); __builtin_amdgcn_s_barrier(); asm volatile("" ::: "memory"); }
; DI void gdn_out(CP c, int l, int item, unsigned char* sm) {
;     ...
;     if (comb) {
;         const int hh = fin ? item - NITEM_GDN : h;
;         const bf16_t* XAg = fin ? (const bf16_t*)(ws + WS_XA256) + (size_t)hh * 16384 : (const bf16_t*)(ws + WS_XA) + (size_t)((n - 128) * 4 + h) * 16384;
;         const bf16_t* XSg = (const bf16_t*)(ws + WS_XS128) + (size_t)hh * 16384;
;         bf16_t* As = Ws; bf16_t* S8s = (bf16_t*)OS;
; #pragma unroll
;         for (int k = 0; k < 4; ++k) { const int v = tid + 512 * k, r = v >> 4, sg = (v & 15) * 8;
;             *(u32x4*)(As + r * 136 + sg) = *(const u32x4*)(XAg + (size_t)v * 8); *(u32x4*)(S8s + r * 136 + sg) = *(const u32x4*)(XSg + (size_t)v * 8); }
;         lds_barrier();
;         bf16x8 Bf[4];
; #pragma unroll
;         for (int s2 = 0; s2 < 4; ++s2) Bf[s2] = *(const bf16x8*)(S8s + (16 * w + fr) * 136 + 32 * s2 + 8 * fq);
; #pragma unroll
;         for (int mt = 0; mt < 8; ++mt) { f32x4 a = (f32x4){0.f, 0.f, 0.f, 0.f};
; #pragma unroll
;             for (int s2 = 0; s2 < 4; ++s2) a = __builtin_amdgcn_mfma_f32_16x16x32_bf16(*(const bf16x8*)(As + (16 * mt + fr) * 136 + 32 * s2 + 8 * fq), Bf[s2], a, 0, 0, 0);
;             if (fin) { float* o = c->out + O_PGDN + ((size_t)l * 4 + hh) * 16384;
; #pragma unroll
;                 for (int i = 0; i < 4; ++i) o[(16 * mt + 4 * fq + i) * 128 + 16 * w + fr] += a[i]; }
;             else { const u32x2 bb = *(const u32x2*)(SNg + (size_t)(16 * w + fr) * 128 + 16 * mt + 4 * fq);
;                 u32x2 p; p.x = pk2(a[0] + lo16(bb.x), a[1] + hi16(bb.x)); p.y = pk2(a[2] + lo16(bb.y), a[3] + hi16(bb.y));
;                 *(u32x2*)(STs + (16 * w + fr) * 136 + 16 * mt + 4 * fq) = p; }
;             asm volatile("" ::: "memory"); }
.LBB0_508:
	v_and_b32_e32 v34, 48, v22
	v_ashrrev_i32_e32 v30, 6, v22
	v_and_b32_e32 v32, 15, v22
	v_bfe_u32 v31, v22, 4, 2
	s_and_b32 s42, s8, 3
	s_andn2_b64 vcc, exec, s[26:27]
	v_add_u32_e32 v33, 0, v34
	s_cbranch_vccnz .LBB0_542
	s_add_i32 s14, s8, 0xfffffb80
	s_and_b64 s[24:25], s[22:23], exec
	s_cselect_b32 s26, s14, s42
	s_and_b32 s24, s8, -4
	s_or_b32 s24, s24, s42
	s_addk_i32 s24, 0xfe00
	s_and_b64 s[22:23], s[22:23], exec
	s_mov_b32 s22, 0x1c6c6000
	s_cselect_b32 s22, s22, 0x1b6c6000
	s_cselect_b32 s14, s14, s24
	s_add_u32 s24, s20, s22
	s_addc_u32 s25, s21, 0
	s_lshl_b64 s[22:23], s[14:15], 15
	s_add_u32 s24, s24, s22
	s_addc_u32 s25, s25, s23
	s_waitcnt vmcnt(0)
	v_lshlrev_b64 v[6:7], 4, v[22:23]
	v_lshl_add_u64 v[2:3], s[24:25], 0, v[6:7]
	global_load_dwordx4 v[72:75], v[2:3], off
	s_mov_b32 s14, s26
	v_and_b32_e32 v38, 0x78, v37
	s_movk_i32 s26, 0x88
	s_lshl_b64 s[22:23], s[14:15], 15
	v_lshlrev_b32_e32 v0, 1, v38
	v_mul_lo_u32 v39, v36, s26
	s_add_u32 s22, s29, s22
	v_add_u32_e32 v8, 0, v0
	v_lshlrev_b32_e32 v9, 1, v39
	s_addc_u32 s23, s30, s23
	v_add_u32_e32 v10, v8, v9
	v_readlane_b32 s27, v253, 62
	v_mul_lo_u32 v40, v35, s26
	s_movk_i32 s26, 0x110
	v_add_u32_e32 v0, s27, v0
	v_lshl_or_b32 v28, v30, 4, v32
	v_mul_lo_u32 v20, v28, s26
	v_ashrrev_i32_e32 v29, 31, v28
	v_lshlrev_b64 v[18:19], 8, v[28:29]
	v_lshl_add_u64 v[18:19], s[12:13], 0, v[18:19]
	v_mad_u32_u24 v29, v32, s26, v33
	s_and_b64 vcc, exec, s[18:19]
	v_mov_b32_e32 v104, v10
	v_lshl_add_u64 v[2:3], s[22:23], 0, v[6:7]
	global_load_dwordx4 v[76:79], v[2:3], off
	v_add_u32_e32 v6, v0, v9
	v_lshlrev_b32_e32 v9, 1, v40
	v_add_u32_e32 v10, v8, v9
	v_mov_b32_e32 v105, v6
	v_lshlrev_b64 v[6:7], 4, v[24:25]
	v_lshl_add_u64 v[2:3], s[24:25], 0, v[6:7]
	global_load_dwordx4 v[80:83], v[2:3], off
	v_mov_b32_e32 v106, v10
	v_lshl_add_u64 v[2:3], s[22:23], 0, v[6:7]
	global_load_dwordx4 v[84:87], v[2:3], off
	v_add_u32_e32 v6, v0, v9
	v_mov_b32_e32 v107, v6
	v_add_u32_e32 v2, 0x400, v22
	v_ashrrev_i32_e32 v3, 31, v2
	v_lshlrev_b64 v[6:7], 4, v[2:3]
	v_lshrrev_b32_e32 v9, 4, v2
	v_lshl_add_u64 v[2:3], s[24:25], 0, v[6:7]
	global_load_dwordx4 v[88:91], v[2:3], off
	v_mul_lo_u32 v9, v9, s26
	v_add_u32_e32 v10, v8, v9
	v_mov_b32_e32 v108, v10
	v_lshl_add_u64 v[2:3], s[22:23], 0, v[6:7]
	global_load_dwordx4 v[92:95], v[2:3], off
	v_add_u32_e32 v6, v0, v9
	v_mov_b32_e32 v109, v6
	v_add_u32_e32 v2, 0x600, v22
	v_ashrrev_i32_e32 v3, 31, v2
	v_lshlrev_b64 v[6:7], 4, v[2:3]
	v_lshrrev_b32_e32 v9, 4, v2
	v_lshl_add_u64 v[2:3], s[24:25], 0, v[6:7]
	global_load_dwordx4 v[96:99], v[2:3], off
	v_mul_lo_u32 v9, v9, s26
	v_add_u32_e32 v8, v8, v9
	v_add_u32_e32 v0, v0, v9
	s_mov_b64 s[24:25], -1
	v_lshl_add_u64 v[2:3], s[22:23], 0, v[6:7]
	global_load_dwordx4 v[100:103], v[2:3], off
	s_waitcnt vmcnt(0)
	ds_write_b128 v104, v[72:75]
	ds_write_b128 v105, v[76:79]
	ds_write_b128 v106, v[80:83]
	ds_write_b128 v107, v[84:87]
	ds_write_b128 v108, v[88:91]
	ds_write_b128 v109, v[92:95]
	ds_write_b128 v8, v[96:99]
	ds_write_b128 v0, v[100:103]
	s_waitcnt lgkmcnt(0)
	s_barrier
	v_add3_u32 v0, s27, v20, v34
	ds_read_b128 v[14:17], v0
	ds_read_b128 v[10:13], v0 offset:64
	ds_read_b128 v[6:9], v0 offset:128
	ds_read_b128 v[2:5], v0 offset:192
	v_lshlrev_b32_e32 v0, 3, v31
	v_lshl_add_u64 v[26:27], v[18:19], 0, v[0:1]
	s_cbranch_vccz .Lsng_skip
	global_load_dwordx2 v[46:47], v[26:27], off
	global_load_dwordx2 v[48:49], v[26:27], off offset:32
	global_load_dwordx2 v[50:51], v[26:27], off offset:64
	global_load_dwordx2 v[52:53], v[26:27], off offset:96
	global_load_dwordx2 v[54:55], v[26:27], off offset:128
	global_load_dwordx2 v[56:57], v[26:27], off offset:160
	global_load_dwordx2 v[58:59], v[26:27], off offset:192
	global_load_dwordx2 v[60:61], v[26:27], off offset:224
.Lsng_skip:
	v_add3_u32 v0, 0, v20, v0
	ds_read_b128 v[18:21], v29
	ds_read_b128 v[42:45], v29 offset:64
	s_waitcnt lgkmcnt(1)
	v_mfma_f32_16x16x32_bf16 v[18:21], v[18:21], v[14:17], 0
	s_waitcnt lgkmcnt(0)
	v_mfma_f32_16x16x32_bf16 v[18:21], v[42:45], v[10:13], v[18:21]
	ds_read_b128 v[42:45], v29 offset:128
	s_waitcnt lgkmcnt(0)
	v_mfma_f32_16x16x32_bf16 v[18:21], v[42:45], v[6:9], v[18:21]
	ds_read_b128 v[42:45], v29 offset:192
	s_waitcnt lgkmcnt(0)
	v_mfma_f32_16x16x32_bf16 v[18:21], v[42:45], v[2:5], v[18:21]
	s_cbranch_vccz .LBB0_511
	s_mov_b64 s[24:25], 0
	s_waitcnt vmcnt(7)
	v_lshlrev_b32_e32 v44, 16, v46
	v_and_b32_e32 v45, 0xffff0000, v46
	s_nop 1
	v_pk_add_f32 v[44:45], v[18:19], v[44:45]
	s_nop 0
	v_cvt_pk_bf16_f32 v42, v44, v45
	v_lshlrev_b32_e32 v44, 16, v47
	v_and_b32_e32 v45, 0xffff0000, v47
	v_pk_add_f32 v[44:45], v[20:21], v[44:45]
	s_nop 0
	v_cvt_pk_bf16_f32 v43, v44, v45
	ds_write_b64 v0, v[42:43] offset:62464

; DI unsigned pk2(float lo, float hi) { const hwf2_t v = {lo, hi}; const hwbf2_t b = __builtin_convertvector(v, hwbf2_t); return __builtin_bit_cast(unsigned, b); }
; DI float lo16(unsigned w) { return __uint_as_float(w << 16); }
; DI float hi16(unsigned w) { return __uint_as_float(w & 0xffff0000u); }
; DI void gdn_out(CP c, int l, int item, unsigned char* sm) {
;     ...
;         for (int mt = 0; mt < 8; ++mt) { f32x4 a = (f32x4){0.f, 0.f, 0.f, 0.f};
; #pragma unroll
;             for (int s2 = 0; s2 < 4; ++s2) a = __builtin_amdgcn_mfma_f32_16x16x32_bf16(*(const bf16x8*)(As + (16 * mt + fr) * 136 + 32 * s2 + 8 * fq), Bf[s2], a, 0, 0, 0);
;             if (fin) { float* o = c->out + O_PGDN + ((size_t)l * 4 + hh) * 16384;
; #pragma unroll
;                 for (int i = 0; i < 4; ++i) o[(16 * mt + 4 * fq + i) * 128 + 16 * w + fr] += a[i]; }
;             else { const u32x2 bb = *(const u32x2*)(SNg + (size_t)(16 * w + fr) * 128 + 16 * mt + 4 * fq);
;                 u32x2 p; p.x = pk2(a[0] + lo16(bb.x), a[1] + hi16(bb.x)); p.y = pk2(a[2] + lo16(bb.y), a[3] + hi16(bb.y));
;                 *(u32x2*)(STs + (16 * w + fr) * 136 + 16 * mt + 4 * fq) = p; }
.LBB0_513:
	s_nop 2
	v_mul_u32_u24_e32 v18, 0x110, v32
	v_add_u32_e32 v29, v33, v18
	ds_read_b128 v[18:21], v29 offset:4352
	ds_read_b128 v[42:45], v29 offset:4416
	v_cndmask_b32_e64 v41, 0, 1, s[18:19]
	s_mov_b64 s[24:25], -1
	v_cmp_ne_u32_e64 s[40:41], 1, v41
	s_andn2_b64 vcc, exec, s[18:19]
	s_waitcnt lgkmcnt(1)
	v_mfma_f32_16x16x32_bf16 v[18:21], v[18:21], v[14:17], 0
	s_waitcnt lgkmcnt(0)
	v_mfma_f32_16x16x32_bf16 v[18:21], v[42:45], v[10:13], v[18:21]
	ds_read_b128 v[42:45], v29 offset:4480
	s_waitcnt lgkmcnt(0)
	v_mfma_f32_16x16x32_bf16 v[18:21], v[42:45], v[6:9], v[18:21]
	ds_read_b128 v[42:45], v29 offset:4544
	s_waitcnt lgkmcnt(0)
	v_mfma_f32_16x16x32_bf16 v[18:21], v[42:45], v[2:5], v[18:21]
	s_cbranch_vccnz .LBB0_515
	s_mov_b64 s[24:25], 0
	s_waitcnt vmcnt(6)
	v_lshlrev_b32_e32 v44, 16, v48
	v_and_b32_e32 v45, 0xffff0000, v48
	s_nop 1
	v_pk_add_f32 v[44:45], v[18:19], v[44:45]
	s_nop 0
	v_cvt_pk_bf16_f32 v42, v44, v45
	v_lshlrev_b32_e32 v44, 16, v49
	v_and_b32_e32 v45, 0xffff0000, v49
	v_pk_add_f32 v[44:45], v[20:21], v[44:45]
	s_nop 0
	v_cvt_pk_bf16_f32 v43, v44, v45
	ds_write_b64 v0, v[42:43] offset:62496

; DI unsigned pk2(float lo, float hi) { const hwf2_t v = {lo, hi}; const hwbf2_t b = __builtin_convertvector(v, hwbf2_t); return __builtin_bit_cast(unsigned, b); }
; DI float lo16(unsigned w) { return __uint_as_float(w << 16); }
; DI float hi16(unsigned w) { return __uint_as_float(w & 0xffff0000u); }
; DI void gdn_out(CP c, int l, int item, unsigned char* sm) {
;     ...
;         for (int mt = 0; mt < 8; ++mt) { f32x4 a = (f32x4){0.f, 0.f, 0.f, 0.f};
; #pragma unroll
;             for (int s2 = 0; s2 < 4; ++s2) a = __builtin_amdgcn_mfma_f32_16x16x32_bf16(*(const bf16x8*)(As + (16 * mt + fr) * 136 + 32 * s2 + 8 * fq), Bf[s2], a, 0, 0, 0);
;             if (fin) { float* o = c->out + O_PGDN + ((size_t)l * 4 + hh) * 16384;
; #pragma unroll
;                 for (int i = 0; i < 4; ++i) o[(16 * mt + 4 * fq + i) * 128 + 16 * w + fr] += a[i]; }
;             else { const u32x2 bb = *(const u32x2*)(SNg + (size_t)(16 * w + fr) * 128 + 16 * mt + 4 * fq);
;                 u32x2 p; p.x = pk2(a[0] + lo16(bb.x), a[1] + hi16(bb.x)); p.y = pk2(a[2] + lo16(bb.y), a[3] + hi16(bb.y));
;                 *(u32x2*)(STs + (16 * w + fr) * 136 + 16 * mt + 4 * fq) = p; }
.LBB0_517:
	s_nop 4
	ds_read_b128 v[18:21], v29 offset:8704
	ds_read_b128 v[42:45], v29 offset:8768
	s_mov_b64 s[24:25], -1
	s_and_b64 vcc, exec, s[40:41]
	s_waitcnt lgkmcnt(1)
	v_mfma_f32_16x16x32_bf16 v[18:21], v[18:21], v[14:17], 0
	s_waitcnt lgkmcnt(0)
	v_mfma_f32_16x16x32_bf16 v[18:21], v[42:45], v[10:13], v[18:21]
	ds_read_b128 v[42:45], v29 offset:8832
	s_waitcnt lgkmcnt(0)
	v_mfma_f32_16x16x32_bf16 v[18:21], v[42:45], v[6:9], v[18:21]
	ds_read_b128 v[42:45], v29 offset:8896
	s_waitcnt lgkmcnt(0)
	v_mfma_f32_16x16x32_bf16 v[18:21], v[42:45], v[2:5], v[18:21]
	s_cbranch_vccnz .LBB0_519
	s_mov_b64 s[24:25], 0
	s_waitcnt vmcnt(5)
	v_lshlrev_b32_e32 v44, 16, v50
	v_and_b32_e32 v45, 0xffff0000, v50
	s_nop 1
	v_pk_add_f32 v[44:45], v[18:19], v[44:45]
	s_nop 0
	v_cvt_pk_bf16_f32 v42, v44, v45
	v_lshlrev_b32_e32 v44, 16, v51
	v_and_b32_e32 v45, 0xffff0000, v51
	v_pk_add_f32 v[44:45], v[20:21], v[44:45]
	s_nop 0
	v_cvt_pk_bf16_f32 v43, v44, v45
	ds_write_b64 v0, v[42:43] offset:62528

; DI unsigned pk2(float lo, float hi) { const hwf2_t v = {lo, hi}; const hwbf2_t b = __builtin_convertvector(v, hwbf2_t); return __builtin_bit_cast(unsigned, b); }
; DI float lo16(unsigned w) { return __uint_as_float(w << 16); }
; DI float hi16(unsigned w) { return __uint_as_float(w & 0xffff0000u); }
; DI void gdn_out(CP c, int l, int item, unsigned char* sm) {
;     ...
;         for (int mt = 0; mt < 8; ++mt) { f32x4 a = (f32x4){0.f, 0.f, 0.f, 0.f};
; #pragma unroll
;             for (int s2 = 0; s2 < 4; ++s2) a = __builtin_amdgcn_mfma_f32_16x16x32_bf16(*(const bf16x8*)(As + (16 * mt + fr) * 136 + 32 * s2 + 8 * fq), Bf[s2], a, 0, 0, 0);
;             if (fin) { float* o = c->out + O_PGDN + ((size_t)l * 4 + hh) * 16384;
; #pragma unroll
;                 for (int i = 0; i < 4; ++i) o[(16 * mt + 4 * fq + i) * 128 + 16 * w + fr] += a[i]; }
;             else { const u32x2 bb = *(const u32x2*)(SNg + (size_t)(16 * w + fr) * 128 + 16 * mt + 4 * fq);
;                 u32x2 p; p.x = pk2(a[0] + lo16(bb.x), a[1] + hi16(bb.x)); p.y = pk2(a[2] + lo16(bb.y), a[3] + hi16(bb.y));
;                 *(u32x2*)(STs + (16 * w + fr) * 136 + 16 * mt + 4 * fq) = p; }
.LBB0_521:
	s_nop 4
	ds_read_b128 v[18:21], v29 offset:13056
	ds_read_b128 v[42:45], v29 offset:13120
	s_mov_b64 s[24:25], -1
	s_and_b64 vcc, exec, s[40:41]
	s_waitcnt lgkmcnt(1)
	v_mfma_f32_16x16x32_bf16 v[18:21], v[18:21], v[14:17], 0
	s_waitcnt lgkmcnt(0)
	v_mfma_f32_16x16x32_bf16 v[18:21], v[42:45], v[10:13], v[18:21]
	ds_read_b128 v[42:45], v29 offset:13184
	s_waitcnt lgkmcnt(0)
	v_mfma_f32_16x16x32_bf16 v[18:21], v[42:45], v[6:9], v[18:21]
	ds_read_b128 v[42:45], v29 offset:13248
	s_waitcnt lgkmcnt(0)
	v_mfma_f32_16x16x32_bf16 v[18:21], v[42:45], v[2:5], v[18:21]
	s_cbranch_vccnz .LBB0_523
	s_mov_b64 s[24:25], 0
	s_waitcnt vmcnt(4)
	v_lshlrev_b32_e32 v44, 16, v52
	v_and_b32_e32 v45, 0xffff0000, v52
	s_nop 1
	v_pk_add_f32 v[44:45], v[18:19], v[44:45]
	s_nop 0
	v_cvt_pk_bf16_f32 v42, v44, v45
	v_lshlrev_b32_e32 v44, 16, v53
	v_and_b32_e32 v45, 0xffff0000, v53
	v_pk_add_f32 v[44:45], v[20:21], v[44:45]
	s_nop 0
	v_cvt_pk_bf16_f32 v43, v44, v45
	ds_write_b64 v0, v[42:43] offset:62560

; DI unsigned pk2(float lo, float hi) { const hwf2_t v = {lo, hi}; const hwbf2_t b = __builtin_convertvector(v, hwbf2_t); return __builtin_bit_cast(unsigned, b); }
; DI float lo16(unsigned w) { return __uint_as_float(w << 16); }
; DI float hi16(unsigned w) { return __uint_as_float(w & 0xffff0000u); }
; DI void gdn_out(CP c, int l, int item, unsigned char* sm) {
;     ...
;         for (int mt = 0; mt < 8; ++mt) { f32x4 a = (f32x4){0.f, 0.f, 0.f, 0.f};
; #pragma unroll
;             for (int s2 = 0; s2 < 4; ++s2) a = __builtin_amdgcn_mfma_f32_16x16x32_bf16(*(const bf16x8*)(As + (16 * mt + fr) * 136 + 32 * s2 + 8 * fq), Bf[s2], a, 0, 0, 0);
;             if (fin) { float* o = c->out + O_PGDN + ((size_t)l * 4 + hh) * 16384;
; #pragma unroll
;                 for (int i = 0; i < 4; ++i) o[(16 * mt + 4 * fq + i) * 128 + 16 * w + fr] += a[i]; }
;             else { const u32x2 bb = *(const u32x2*)(SNg + (size_t)(16 * w + fr) * 128 + 16 * mt + 4 * fq);
;                 u32x2 p; p.x = pk2(a[0] + lo16(bb.x), a[1] + hi16(bb.x)); p.y = pk2(a[2] + lo16(bb.y), a[3] + hi16(bb.y));
;                 *(u32x2*)(STs + (16 * w + fr) * 136 + 16 * mt + 4 * fq) = p; }
.LBB0_525:
	s_nop 4
	ds_read_b128 v[18:21], v29 offset:17408
	ds_read_b128 v[42:45], v29 offset:17472
	s_mov_b64 s[24:25], -1
	s_and_b64 vcc, exec, s[40:41]
	s_waitcnt lgkmcnt(1)
	v_mfma_f32_16x16x32_bf16 v[18:21], v[18:21], v[14:17], 0
	s_waitcnt lgkmcnt(0)
	v_mfma_f32_16x16x32_bf16 v[18:21], v[42:45], v[10:13], v[18:21]
	ds_read_b128 v[42:45], v29 offset:17536
	s_waitcnt lgkmcnt(0)
	v_mfma_f32_16x16x32_bf16 v[18:21], v[42:45], v[6:9], v[18:21]
	ds_read_b128 v[42:45], v29 offset:17600
	s_waitcnt lgkmcnt(0)
	v_mfma_f32_16x16x32_bf16 v[18:21], v[42:45], v[2:5], v[18:21]
	s_cbranch_vccnz .LBB0_527
	s_mov_b64 s[24:25], 0
	s_waitcnt vmcnt(3)
	v_lshlrev_b32_e32 v44, 16, v54
	v_and_b32_e32 v45, 0xffff0000, v54
	s_nop 1
	v_pk_add_f32 v[44:45], v[18:19], v[44:45]
	s_nop 0
	v_cvt_pk_bf16_f32 v42, v44, v45
	v_lshlrev_b32_e32 v44, 16, v55
	v_and_b32_e32 v45, 0xffff0000, v55
	v_pk_add_f32 v[44:45], v[20:21], v[44:45]
	s_nop 0
	v_cvt_pk_bf16_f32 v43, v44, v45
	ds_write_b64 v0, v[42:43] offset:62592

; DI unsigned pk2(float lo, float hi) { const hwf2_t v = {lo, hi}; const hwbf2_t b = __builtin_convertvector(v, hwbf2_t); return __builtin_bit_cast(unsigned, b); }
; DI float lo16(unsigned w) { return __uint_as_float(w << 16); }
; DI float hi16(unsigned w) { return __uint_as_float(w & 0xffff0000u); }
; DI void gdn_out(CP c, int l, int item, unsigned char* sm) {
;     ...
;         for (int mt = 0; mt < 8; ++mt) { f32x4 a = (f32x4){0.f, 0.f, 0.f, 0.f};
; #pragma unroll
;             for (int s2 = 0; s2 < 4; ++s2) a = __builtin_amdgcn_mfma_f32_16x16x32_bf16(*(const bf16x8*)(As + (16 * mt + fr) * 136 + 32 * s2 + 8 * fq), Bf[s2], a, 0, 0, 0);
;             if (fin) { float* o = c->out + O_PGDN + ((size_t)l * 4 + hh) * 16384;
; #pragma unroll
;                 for (int i = 0; i < 4; ++i) o[(16 * mt + 4 * fq + i) * 128 + 16 * w + fr] += a[i]; }
;             else { const u32x2 bb = *(const u32x2*)(SNg + (size_t)(16 * w + fr) * 128 + 16 * mt + 4 * fq);
;                 u32x2 p; p.x = pk2(a[0] + lo16(bb.x), a[1] + hi16(bb.x)); p.y = pk2(a[2] + lo16(bb.y), a[3] + hi16(bb.y));
;                 *(u32x2*)(STs + (16 * w + fr) * 136 + 16 * mt + 4 * fq) = p; }
.LBB0_529:
	s_nop 4
	ds_read_b128 v[18:21], v29 offset:21760
	ds_read_b128 v[42:45], v29 offset:21824
	s_mov_b64 s[24:25], -1
	s_and_b64 vcc, exec, s[40:41]
	s_waitcnt lgkmcnt(1)
	v_mfma_f32_16x16x32_bf16 v[18:21], v[18:21], v[14:17], 0
	s_waitcnt lgkmcnt(0)
	v_mfma_f32_16x16x32_bf16 v[18:21], v[42:45], v[10:13], v[18:21]
	ds_read_b128 v[42:45], v29 offset:21888
	s_waitcnt lgkmcnt(0)
	v_mfma_f32_16x16x32_bf16 v[18:21], v[42:45], v[6:9], v[18:21]
	ds_read_b128 v[42:45], v29 offset:21952
	s_waitcnt lgkmcnt(0)
	v_mfma_f32_16x16x32_bf16 v[18:21], v[42:45], v[2:5], v[18:21]
	s_cbranch_vccnz .LBB0_531
	s_mov_b64 s[24:25], 0
	s_waitcnt vmcnt(2)
	v_lshlrev_b32_e32 v44, 16, v56
	v_and_b32_e32 v45, 0xffff0000, v56
	s_nop 1
	v_pk_add_f32 v[44:45], v[18:19], v[44:45]
	s_nop 0
	v_cvt_pk_bf16_f32 v42, v44, v45
	v_lshlrev_b32_e32 v44, 16, v57
	v_and_b32_e32 v45, 0xffff0000, v57
	v_pk_add_f32 v[44:45], v[20:21], v[44:45]
	s_nop 0
	v_cvt_pk_bf16_f32 v43, v44, v45
	ds_write_b64 v0, v[42:43] offset:62624

; DI unsigned pk2(float lo, float hi) { const hwf2_t v = {lo, hi}; const hwbf2_t b = __builtin_convertvector(v, hwbf2_t); return __builtin_bit_cast(unsigned, b); }
; DI float lo16(unsigned w) { return __uint_as_float(w << 16); }
; DI float hi16(unsigned w) { return __uint_as_float(w & 0xffff0000u); }
; DI void gdn_out(CP c, int l, int item, unsigned char* sm) {
;     ...
;         for (int mt = 0; mt < 8; ++mt) { f32x4 a = (f32x4){0.f, 0.f, 0.f, 0.f};
; #pragma unroll
;             for (int s2 = 0; s2 < 4; ++s2) a = __builtin_amdgcn_mfma_f32_16x16x32_bf16(*(const bf16x8*)(As + (16 * mt + fr) * 136 + 32 * s2 + 8 * fq), Bf[s2], a, 0, 0, 0);
;             if (fin) { float* o = c->out + O_PGDN + ((size_t)l * 4 + hh) * 16384;
; #pragma unroll
;                 for (int i = 0; i < 4; ++i) o[(16 * mt + 4 * fq + i) * 128 + 16 * w + fr] += a[i]; }
;             else { const u32x2 bb = *(const u32x2*)(SNg + (size_t)(16 * w + fr) * 128 + 16 * mt + 4 * fq);
;                 u32x2 p; p.x = pk2(a[0] + lo16(bb.x), a[1] + hi16(bb.x)); p.y = pk2(a[2] + lo16(bb.y), a[3] + hi16(bb.y));
;                 *(u32x2*)(STs + (16 * w + fr) * 136 + 16 * mt + 4 * fq) = p; }
.LBB0_533:
	s_nop 4
	ds_read_b128 v[18:21], v29 offset:26112
	ds_read_b128 v[42:45], v29 offset:26176
	s_mov_b64 s[24:25], -1
	s_and_b64 vcc, exec, s[40:41]
	s_waitcnt lgkmcnt(1)
	v_mfma_f32_16x16x32_bf16 v[18:21], v[18:21], v[14:17], 0
	s_waitcnt lgkmcnt(0)
	v_mfma_f32_16x16x32_bf16 v[18:21], v[42:45], v[10:13], v[18:21]
	ds_read_b128 v[42:45], v29 offset:26240
	s_waitcnt lgkmcnt(0)
	v_mfma_f32_16x16x32_bf16 v[18:21], v[42:45], v[6:9], v[18:21]
	ds_read_b128 v[42:45], v29 offset:26304
	s_waitcnt lgkmcnt(0)
	v_mfma_f32_16x16x32_bf16 v[18:21], v[42:45], v[2:5], v[18:21]
	s_cbranch_vccnz .LBB0_535
	s_mov_b64 s[24:25], 0
	s_waitcnt vmcnt(1)
	v_lshlrev_b32_e32 v44, 16, v58
	v_and_b32_e32 v45, 0xffff0000, v58
	s_nop 1
	v_pk_add_f32 v[44:45], v[18:19], v[44:45]
	s_nop 0
	v_cvt_pk_bf16_f32 v42, v44, v45
	v_lshlrev_b32_e32 v44, 16, v59
	v_and_b32_e32 v45, 0xffff0000, v59
	v_pk_add_f32 v[44:45], v[20:21], v[44:45]
	s_nop 0
	v_cvt_pk_bf16_f32 v43, v44, v45
	ds_write_b64 v0, v[42:43] offset:62656

; DI unsigned pk2(float lo, float hi) { const hwf2_t v = {lo, hi}; const hwbf2_t b = __builtin_convertvector(v, hwbf2_t); return __builtin_bit_cast(unsigned, b); }
; DI float lo16(unsigned w) { return __uint_as_float(w << 16); }
; DI float hi16(unsigned w) { return __uint_as_float(w & 0xffff0000u); }
; DI void gdn_out(CP c, int l, int item, unsigned char* sm) {
;     ...
;         for (int mt = 0; mt < 8; ++mt) { f32x4 a = (f32x4){0.f, 0.f, 0.f, 0.f};
; #pragma unroll
;             for (int s2 = 0; s2 < 4; ++s2) a = __builtin_amdgcn_mfma_f32_16x16x32_bf16(*(const bf16x8*)(As + (16 * mt + fr) * 136 + 32 * s2 + 8 * fq), Bf[s2], a, 0, 0, 0);
;             if (fin) { float* o = c->out + O_PGDN + ((size_t)l * 4 + hh) * 16384;
; #pragma unroll
;                 for (int i = 0; i < 4; ++i) o[(16 * mt + 4 * fq + i) * 128 + 16 * w + fr] += a[i]; }
;             else { const u32x2 bb = *(const u32x2*)(SNg + (size_t)(16 * w + fr) * 128 + 16 * mt + 4 * fq);
;                 u32x2 p; p.x = pk2(a[0] + lo16(bb.x), a[1] + hi16(bb.x)); p.y = pk2(a[2] + lo16(bb.y), a[3] + hi16(bb.y));
;                 *(u32x2*)(STs + (16 * w + fr) * 136 + 16 * mt + 4 * fq) = p; }
.LBB0_537:
	s_nop 4
	ds_read_b128 v[18:21], v29 offset:30464
	s_and_b64 vcc, exec, s[40:41]
	s_mov_b64 s[24:25], -1
	s_waitcnt lgkmcnt(0)
	v_mfma_f32_16x16x32_bf16 v[14:17], v[18:21], v[14:17], 0
	ds_read_b128 v[18:21], v29 offset:30528
	s_waitcnt lgkmcnt(0)
	v_mfma_f32_16x16x32_bf16 v[10:13], v[18:21], v[10:13], v[14:17]
	s_nop 4
	ds_read_b128 v[14:17], v29 offset:30592
	s_waitcnt lgkmcnt(0)
	v_mfma_f32_16x16x32_bf16 v[6:9], v[14:17], v[6:9], v[10:13]
	s_nop 2
	ds_read_b128 v[10:13], v29 offset:30656
	s_waitcnt lgkmcnt(0)
	v_mfma_f32_16x16x32_bf16 v[2:5], v[10:13], v[2:5], v[6:9]
	s_cbranch_vccnz .LBB0_539
	s_nop 1
	s_mov_b64 s[24:25], 0
	s_waitcnt vmcnt(0)
	v_lshlrev_b32_e32 v8, 16, v60
	v_and_b32_e32 v9, 0xffff0000, v60
	v_pk_add_f32 v[8:9], v[2:3], v[8:9]
	s_nop 0
	v_cvt_pk_bf16_f32 v6, v8, v9
	v_lshlrev_b32_e32 v8, 16, v61
	v_and_b32_e32 v9, 0xffff0000, v61
	v_pk_add_f32 v[8:9], v[4:5], v[8:9]
	s_nop 0
	v_cvt_pk_bf16_f32 v7, v8, v9
	ds_write_b64 v0, v[6:7] offset:62688
